# row_pass: register software-prefetch of next iteration x/Y rows (issued mid-iteration), lng/lnb reload removed, store-drain waits removed; on top of v40
# speedup vs baseline: 1.0492x; 1.0021x over previous
; DI void row_pass2(const RowPass& P, int m0, int m1, bool act1, int lane) {
;     const RowRef A = row_ref(P, m0, true), B = row_ref(P, m1, act1);
;     if (!A.act && !B.act) return;
;     f32x4 va[4], vb[4]; rp_load(A, va, lane); rp_load(B, vb, lane);
;     if (P.Y) {
;         u32x2 ya[4], yb[4]; rp_loady(P, A, ya, lane); rp_loady(P, B, yb, lane);
;         rp_mix(P, A, va, ya, lane); rp_mix(P, B, vb, yb, lane);
; __global__ void __launch_bounds__(512, 2) fwd_kernel(Args a) {
;     ...
;         if (get_rowpass(ph, a, P)) { for (int m = gw; m < ROWS; m += 2 * NGW) { const int m1 = m + NGW; const bool v1 = m1 < ROWS; row_pass2(P, m, v1 ? m1 : m, v1, lane); } }
.LBB0_155:
	s_ashr_i32 s4, s13, 6
	v_readlane_b32 s5, v245, 16
	s_add_i32 s76, s4, s5
	s_cmp_lt_i32 s76, 0x8400
	v_readlane_b32 s0, v241, 53
	s_cselect_b64 s[22:23], -1, 0
	v_readlane_b32 s1, v241, 54
	s_and_b64 s[0:1], s[0:1], s[22:23]
	s_andn2_b64 vcc, exec, s[0:1]
	v_and_b32_e32 v189, 63, v188
	s_cbranch_vccnz .LBB0_177
	v_readlane_b32 s0, v241, 49
	s_cmp_eq_u32 s0, 0
	v_readlane_b32 s0, v241, 31
	v_readlane_b32 s4, v241, 29
	s_cselect_b64 s[20:21], -1, 0
	v_readlane_b32 s1, v241, 32
	v_readlane_b32 s5, v241, 30
	s_sub_u32 s56, s0, s4
	s_subb_u32 s57, s1, s5
	v_readlane_b32 s0, v241, 35
	v_readlane_b32 s6, v241, 33
	v_readlane_b32 s1, v241, 36
	v_readlane_b32 s7, v241, 34
	s_sub_u32 s30, s0, s6
	s_subb_u32 s31, s1, s7
	v_readlane_b32 s0, v241, 37
	v_readlane_b32 s1, v241, 38
	v_lshlrev_b32_e32 v156, 3, v189
	s_cmp_lg_u64 s[0:1], 0
	v_lshl_add_u64 v[54:55], s[0:1], 0, v[156:157]
	v_readlane_b32 s0, v242, 13
	v_readlane_b32 s1, v242, 14
	s_cselect_b64 s[40:41], -1, 0
	s_mov_b32 s4, s0
	s_ashr_i32 s5, s0, 31
	v_writelane_b32 v242, s0, 13
	s_waitcnt vmcnt(0)
	v_lshlrev_b32_e32 v0, 4, v189
	v_mov_b32_e32 v1, v157
	v_writelane_b32 v242, s1, 14
	s_lshl_b64 s[0:1], s[4:5], 2
	v_readlane_b32 s4, v241, 39
	v_readlane_b32 s5, v241, 40
	s_add_u32 s0, s4, s0
	s_addc_u32 s1, s5, s1
	v_lshl_add_u64 v[56:57], s[0:1], 0, v[0:1]
	v_readlane_b32 s0, v241, 41
	v_readlane_b32 s1, v241, 42
	s_cmp_lg_u64 s[6:7], 0
	v_readlane_b32 s4, v242, 11
	v_lshl_add_u64 v[58:59], s[0:1], 0, v[0:1]
	v_readlane_b32 s0, v241, 43
	v_readlane_b32 s1, v241, 44
	s_cselect_b64 s[42:43], -1, 0
	v_readlane_b32 s5, v242, 12
	v_lshl_add_u64 v[60:61], s[0:1], 0, v[0:1]
	v_readlane_b32 s0, v241, 47
	v_readlane_b32 s1, v241, 48
	s_cmp_lg_u64 s[0:1], 0
	s_cselect_b64 s[44:45], -1, 0
	s_ashr_i32 s5, s4, 31
	v_writelane_b32 v242, s4, 11
	v_lshlrev_b32_e32 v52, 2, v189
	v_lshl_add_u64 v[62:63], s[0:1], 0, v[156:157]
	v_writelane_b32 v242, s5, 12
	s_mov_b32 s46, s76
	v_readlane_b32 s4, v242, 9
	v_readlane_b32 s5, v242, 10
	s_ashr_i32 s5, s4, 31
	v_writelane_b32 v242, s4, 9
	s_nop 1
	v_writelane_b32 v242, s5, 10
	s_mov_b32 s25, -1
	s_branch .LBB0_158

; DI float bflo(unsigned w) { return __uint_as_float(w << 16); }
; DI float bfhi(unsigned w) { return __uint_as_float(w & 0xffff0000u); }
; DI void rp_load(const RowRef& R, f32x4 (&v)[4], int lane) {
; #pragma unroll
;     for (int jj = 0; jj < 4; ++jj) v[jj] = *(const f32x4*)(R.xs + 4 * lane + 256 * jj);
; }
; DI void rp_loady(const RowPass& P, const RowRef& R, u32x2 (&yw)[4], int lane) {
; #pragma unroll
;     for (int jj = 0; jj < 4; ++jj) yw[jj] = *(const u32x2*)(P.Y + (size_t)R.m * DM + 4 * lane + 256 * jj);
; }
; DI void rp_mix(const RowPass& P, const RowRef& R, f32x4 (&v)[4], const u32x2 (&yw)[4], int lane) {
;     const float* gate = P.mod + (size_t)R.cls * 6144 + P.gate_off;
; #pragma unroll
;     for (int jj = 0; jj < 4; ++jj) { const int c0 = 4 * lane + 256 * jj; const f32x4 g = *(const f32x4*)(gate + c0);
;         v[jj][0] = DN_ALPHA * v[jj][0] + g[0] * bflo(yw[jj].x); v[jj][1] = DN_ALPHA * v[jj][1] + g[1] * bfhi(yw[jj].x);
;         v[jj][2] = DN_ALPHA * v[jj][2] + g[2] * bflo(yw[jj].y); v[jj][3] = DN_ALPHA * v[jj][3] + g[3] * bfhi(yw[jj].y); }
.LBB0_166:
	s_or_b64 s[4:5], s[20:21], s[60:61]
	s_and_b64 s[60:61], s[38:39], s[4:5]
	s_or_b64 s[64:65], s[20:21], s[26:27]
	s_or_b64 s[4:5], s[64:65], s[60:61]
	s_andn2_b64 vcc, exec, s[4:5]
	s_cbranch_vccnz .LBB0_157
	s_ashr_i32 s67, s66, 31
	s_ashr_i32 s91, s90, 31
	v_readlane_b32 s8, v241, 29
	v_readlane_b32 s9, v241, 30
	s_add_u32 s1, s8, s36
	s_addc_u32 s6, s9, s37
	s_lshl_b64 s[4:5], s[90:91], 12
	s_add_u32 s4, s1, s4
	s_addc_u32 s5, s6, s5
	s_add_u32 s1, s8, s28
	s_addc_u32 s8, s9, s29
	s_lshl_b64 s[6:7], s[66:67], 12
	s_add_u32 s6, s1, s6
	v_lshlrev_b32_e32 v53, 2, v52
	s_addc_u32 s7, s8, s7
	s_cmp_eq_u32 s25, s46
	s_cbranch_scc1 rp_pf_x
	global_load_dwordx4 v[28:31], v53, s[4:5]
	global_load_dwordx4 v[24:27], v53, s[4:5] offset:1024
	global_load_dwordx4 v[20:23], v53, s[4:5] offset:2048
	global_load_dwordx4 v[16:19], v53, s[4:5] offset:3072
	s_waitcnt lgkmcnt(0)
	global_load_dwordx4 v[12:15], v53, s[6:7]
	global_load_dwordx4 v[8:11], v53, s[6:7] offset:1024
	global_load_dwordx4 v[4:7], v53, s[6:7] offset:2048
	global_load_dwordx4 v[0:3], v53, s[6:7] offset:3072
	s_branch rp_pf_xj
rp_pf_x:
	s_waitcnt vmcnt(0) lgkmcnt(0)
	v_mov_b32_e32 v28, v208
	v_mov_b32_e32 v29, v209
	v_mov_b32_e32 v30, v210
	v_mov_b32_e32 v31, v211
	v_mov_b32_e32 v24, v212
	v_mov_b32_e32 v25, v213
	v_mov_b32_e32 v26, v214
	v_mov_b32_e32 v27, v215
	v_mov_b32_e32 v20, v216
	v_mov_b32_e32 v21, v217
	v_mov_b32_e32 v22, v218
	v_mov_b32_e32 v23, v219
	v_mov_b32_e32 v16, v220
	v_mov_b32_e32 v17, v221
	v_mov_b32_e32 v18, v222
	v_mov_b32_e32 v19, v223
	v_mov_b32_e32 v12, v224
	v_mov_b32_e32 v13, v225
	v_mov_b32_e32 v14, v226
	v_mov_b32_e32 v15, v227
	v_mov_b32_e32 v8, v228
	v_mov_b32_e32 v9, v229
	v_mov_b32_e32 v10, v230
	v_mov_b32_e32 v11, v231
	v_mov_b32_e32 v4, v232
	v_mov_b32_e32 v5, v233
	v_mov_b32_e32 v6, v234
	v_mov_b32_e32 v7, v235
	v_mov_b32_e32 v0, v236
	v_mov_b32_e32 v1, v237
	v_mov_b32_e32 v2, v238
	v_mov_b32_e32 v3, v239
rp_pf_xj:
	s_andn2_b64 vcc, exec, s[40:41]
	s_cbranch_vccnz rp_noy_wait
	s_ashr_i32 s47, s46, 31
	s_lshl_b64 s[4:5], s[46:47], 11
	s_ashr_i32 s1, s0, 31
	s_cmp_eq_u32 s25, s46
	s_cbranch_scc1 rp_pf_y
	v_lshl_add_u64 v[32:33], v[54:55], 0, s[4:5]
	s_lshl_b64 s[0:1], s[0:1], 11
	global_load_dwordx2 v[72:73], v[32:33], off
	global_load_dwordx2 v[74:75], v[32:33], off offset:512
	global_load_dwordx2 v[76:77], v[32:33], off offset:1024
	global_load_dwordx2 v[82:83], v[32:33], off offset:1536
	v_lshl_add_u64 v[32:33], v[54:55], 0, s[0:1]
	global_load_dwordx2 v[84:85], v[32:33], off
	global_load_dwordx2 v[86:87], v[32:33], off offset:512
	global_load_dwordx2 v[88:89], v[32:33], off offset:1024
	global_load_dwordx2 v[90:91], v[32:33], off offset:1536
	s_branch rp_pf_yj
rp_pf_y:
	v_mov_b32_e32 v72, v190
	v_mov_b32_e32 v73, v191
	v_mov_b32_e32 v74, v192
	v_mov_b32_e32 v75, v193
	v_mov_b32_e32 v76, v194
	v_mov_b32_e32 v77, v195
	v_mov_b32_e32 v82, v196
	v_mov_b32_e32 v83, v197
	v_mov_b32_e32 v84, v198
	v_mov_b32_e32 v85, v199
	v_mov_b32_e32 v86, v200
	v_mov_b32_e32 v87, v201
	v_mov_b32_e32 v88, v202
	v_mov_b32_e32 v89, v203
	v_mov_b32_e32 v90, v158
	v_mov_b32_e32 v91, v159
rp_pf_yj:
	v_lshl_add_u64 v[44:45], v[56:57], 0, s[62:63]
	v_lshl_add_u64 v[78:79], v[56:57], 0, s[58:59]
	global_load_dwordx4 v[32:35], v[44:45], off
	global_load_dwordx4 v[36:39], v[44:45], off offset:1024
	global_load_dwordx4 v[40:43], v[44:45], off offset:2048
	s_nop 0
	global_load_dwordx4 v[44:47], v[44:45], off offset:3072
	s_nop 0
	global_load_dwordx4 v[48:51], v[78:79], off
	global_load_dwordx4 v[64:67], v[78:79], off offset:1024
	global_load_dwordx4 v[68:71], v[78:79], off offset:2048
	s_nop 0
	global_load_dwordx4 v[78:81], v[78:79], off offset:3072
	s_mov_b32 s0, 0x3fb504f3
	s_waitcnt vmcnt(15)
	v_lshlrev_b32_e32 v92, 16, v72
	v_and_b32_e32 v93, 0xffff0000, v72
	v_lshlrev_b32_e32 v72, 16, v73
	v_and_b32_e32 v73, 0xffff0000, v73
	s_waitcnt vmcnt(11)
	v_lshlrev_b32_e32 v100, 16, v84
	v_and_b32_e32 v101, 0xffff0000, v84
	v_lshlrev_b32_e32 v84, 16, v85
	v_and_b32_e32 v85, 0xffff0000, v85
	s_waitcnt vmcnt(10)
	v_lshlrev_b32_e32 v102, 16, v86
	v_and_b32_e32 v103, 0xffff0000, v86
	s_waitcnt vmcnt(8)
	v_lshlrev_b32_e32 v106, 16, v90
	v_and_b32_e32 v107, 0xffff0000, v90
	v_lshlrev_b32_e32 v94, 16, v74
	v_and_b32_e32 v95, 0xffff0000, v74
	v_lshlrev_b32_e32 v74, 16, v75
	v_and_b32_e32 v75, 0xffff0000, v75
	v_lshlrev_b32_e32 v86, 16, v87
	v_and_b32_e32 v87, 0xffff0000, v87
	v_lshlrev_b32_e32 v90, 16, v91
	v_and_b32_e32 v91, 0xffff0000, v91
	s_waitcnt vmcnt(7)
	v_pk_mul_f32 v[32:33], v[32:33], v[92:93]
	v_pk_mul_f32 v[34:35], v[34:35], v[72:73]
	s_waitcnt vmcnt(3)
	v_pk_mul_f32 v[50:51], v[50:51], v[84:85]
	s_waitcnt vmcnt(2)
	v_pk_mul_f32 v[64:65], v[64:65], v[102:103]
	s_waitcnt vmcnt(0)
; DI float bflo(unsigned w) { return __uint_as_float(w << 16); }
; DI float bfhi(unsigned w) { return __uint_as_float(w & 0xffff0000u); }
; DI void rp_mix(const RowPass& P, const RowRef& R, f32x4 (&v)[4], const u32x2 (&yw)[4], int lane) {
;     const float* gate = P.mod + (size_t)R.cls * 6144 + P.gate_off;
; #pragma unroll
;     for (int jj = 0; jj < 4; ++jj) { const int c0 = 4 * lane + 256 * jj; const f32x4 g = *(const f32x4*)(gate + c0);
;         v[jj][0] = DN_ALPHA * v[jj][0] + g[0] * bflo(yw[jj].x); v[jj][1] = DN_ALPHA * v[jj][1] + g[1] * bfhi(yw[jj].x);
;         v[jj][2] = DN_ALPHA * v[jj][2] + g[2] * bflo(yw[jj].y); v[jj][3] = DN_ALPHA * v[jj][3] + g[3] * bfhi(yw[jj].y); }
; }
; DI void rp_stats2(const f32x4 (&va)[4], const f32x4 (&vb)[4], float& ma, float& ra, float& mb, float& rb) {
;     float sa = 0.f, sb = 0.f;
; #pragma unroll
;     for (int j = 0; j < 4; ++j) { sa += (va[j][0] + va[j][1]) + (va[j][2] + va[j][3]); sb += (vb[j][0] + vb[j][1]) + (vb[j][2] + vb[j][3]); }
;     wave_sum2(sa, sb); ma = sa * (1.0f / DM); mb = sb * (1.0f / DM);
;     float qa = 0.f, qb = 0.f;
; #pragma unroll
;     for (int j = 0; j < 4; ++j) { const f32x4 da = va[j] - ma, db = vb[j] - mb; qa += (da[0] * da[0] + da[1] * da[1]) + (da[2] * da[2] + da[3] * da[3]); qb += (db[0] * db[0] + db[1] * db[1]) + (db[2] * db[2] + db[3] * db[3]); }
;     wave_sum2(qa, qb); ra = 1.0f / sqrtf(qa * (1.0f / DM) + LN_EPS); rb = 1.0f / sqrtf(qb * (1.0f / DM) + LN_EPS);
	v_pk_mul_f32 v[84:85], v[78:79], v[106:107]
	v_lshlrev_b32_e32 v96, 16, v76
	v_and_b32_e32 v97, 0xffff0000, v76
	v_lshlrev_b32_e32 v76, 16, v77
	v_and_b32_e32 v77, 0xffff0000, v77
	v_lshlrev_b32_e32 v104, 16, v88
	v_and_b32_e32 v105, 0xffff0000, v88
	v_pk_mul_f32 v[38:39], v[38:39], v[74:75]
	v_pk_mul_f32 v[48:49], v[48:49], v[100:101]
	v_pk_mul_f32 v[66:67], v[66:67], v[86:87]
	v_pk_fma_f32 v[28:29], v[28:29], s[0:1], v[32:33] op_sel_hi:[1,0,1]
	v_pk_fma_f32 v[30:31], v[30:31], s[0:1], v[34:35] op_sel_hi:[1,0,1]
	v_pk_fma_f32 v[74:75], v[8:9], s[0:1], v[64:65] op_sel_hi:[1,0,1]
	v_pk_fma_f32 v[64:65], v[0:1], s[0:1], v[84:85] op_sel_hi:[1,0,1]
	v_pk_mul_f32 v[0:1], v[80:81], v[90:91]
	v_lshlrev_b32_e32 v98, 16, v82
	v_and_b32_e32 v99, 0xffff0000, v82
	v_lshlrev_b32_e32 v82, 16, v83
	v_and_b32_e32 v83, 0xffff0000, v83
	v_lshlrev_b32_e32 v88, 16, v89
	v_and_b32_e32 v89, 0xffff0000, v89
	v_pk_mul_f32 v[36:37], v[36:37], v[94:95]
	v_pk_mul_f32 v[42:43], v[42:43], v[76:77]
	v_pk_mul_f32 v[68:69], v[68:69], v[104:105]
	v_pk_fma_f32 v[76:77], v[12:13], s[0:1], v[48:49] op_sel_hi:[1,0,1]
	v_pk_fma_f32 v[12:13], v[14:15], s[0:1], v[50:51] op_sel_hi:[1,0,1]
	v_pk_fma_f32 v[72:73], v[10:11], s[0:1], v[66:67] op_sel_hi:[1,0,1]
	v_pk_fma_f32 v[66:67], v[2:3], s[0:1], v[0:1] op_sel_hi:[1,0,1]
	v_mov_b32_e32 v0, v28
	v_mov_b32_e32 v1, v30
	v_mov_b32_e32 v2, v29
	v_mov_b32_e32 v3, v31
	v_pk_mul_f32 v[46:47], v[46:47], v[82:83]
	v_pk_mul_f32 v[82:83], v[70:71], v[88:89]
	v_pk_fma_f32 v[24:25], v[24:25], s[0:1], v[36:37] op_sel_hi:[1,0,1]
	v_pk_fma_f32 v[26:27], v[26:27], s[0:1], v[38:39] op_sel_hi:[1,0,1]
	v_pk_fma_f32 v[70:71], v[4:5], s[0:1], v[68:69] op_sel_hi:[1,0,1]
	v_pk_add_f32 v[0:1], v[0:1], v[2:3]
	v_mov_b32_e32 v2, v76
	v_mov_b32_e32 v3, v12
	v_mov_b32_e32 v4, v77
	v_mov_b32_e32 v5, v13
	v_pk_mul_f32 v[40:41], v[40:41], v[96:97]
	v_pk_fma_f32 v[68:69], v[6:7], s[0:1], v[82:83] op_sel_hi:[1,0,1]
	v_pk_add_f32 v[2:3], v[2:3], v[4:5]
	v_mov_b32_e32 v4, v24
	v_mov_b32_e32 v5, v26
	v_mov_b32_e32 v6, v25
	v_mov_b32_e32 v7, v27
	v_pk_mul_f32 v[44:45], v[44:45], v[98:99]
	v_pk_fma_f32 v[20:21], v[20:21], s[0:1], v[40:41] op_sel_hi:[1,0,1]
	v_pk_fma_f32 v[22:23], v[22:23], s[0:1], v[42:43] op_sel_hi:[1,0,1]
	v_pk_add_f32 v[4:5], v[4:5], v[6:7]
	v_mov_b32_e32 v6, v74
	v_mov_b32_e32 v7, v72
	v_mov_b32_e32 v8, v75
	v_mov_b32_e32 v9, v73
	v_pk_fma_f32 v[78:79], v[16:17], s[0:1], v[44:45] op_sel_hi:[1,0,1]
	v_pk_fma_f32 v[16:17], v[18:19], s[0:1], v[46:47] op_sel_hi:[1,0,1]
	v_add_f32_e32 v0, v0, v1
	v_add_f32_e32 v1, v2, v3
	v_pk_add_f32 v[4:5], v[4:5], v[4:5] op_sel:[0,1] op_sel_hi:[1,0]
	v_pk_add_f32 v[6:7], v[6:7], v[8:9]
	v_pk_add_f32 v[8:9], v[20:21], v[20:21] op_sel:[0,1] op_sel_hi:[1,0]
	v_pk_add_f32 v[10:11], v[22:23], v[22:23] op_sel:[0,1] op_sel_hi:[1,0]
	v_add_f32_e32 v0, 0, v0
	v_add_f32_e32 v2, 0, v1
	v_mov_b32_e32 v1, v78
	v_mov_b32_e32 v5, v79
	v_mov_b32_e32 v9, v16
	v_mov_b32_e32 v11, v17
	v_pk_add_f32 v[6:7], v[6:7], v[6:7] op_sel:[0,1] op_sel_hi:[1,0]
	v_pk_add_f32 v[14:15], v[70:71], v[70:71] op_sel:[0,1] op_sel_hi:[1,0]
	v_pk_add_f32 v[18:19], v[68:69], v[68:69] op_sel:[0,1] op_sel_hi:[1,0]
	v_pk_add_f32 v[0:1], v[0:1], v[4:5]
	v_pk_add_f32 v[4:5], v[8:9], v[10:11]
	v_mov_b32_e32 v3, v64
	v_pk_add_f32 v[0:1], v[0:1], v[4:5]
	v_mov_b32_e32 v7, v65
	v_mov_b32_e32 v15, v66
	v_mov_b32_e32 v19, v67
	v_add_f32_e32 v4, v0, v1
	v_pk_add_f32 v[0:1], v[2:3], v[6:7]
	v_pk_add_f32 v[2:3], v[14:15], v[18:19]
	s_nop 0
	v_pk_add_f32 v[0:1], v[0:1], v[2:3]
	v_xor_b32_e32 v2, 1, v186
	v_add_f32_e32 v0, v0, v1
	v_and_b32_e32 v1, 64, v186
	v_add_u32_e32 v1, 64, v1
	v_cmp_lt_i32_e32 vcc, v2, v1
	s_nop 1
	v_cndmask_b32_e32 v2, v186, v2, vcc
	v_lshlrev_b32_e32 v14, 2, v2
	ds_bpermute_b32 v3, v14, v0
	ds_bpermute_b32 v2, v14, v4
	s_waitcnt lgkmcnt(1)
	v_add_f32_e32 v0, v0, v3
	v_xor_b32_e32 v3, 2, v186
	v_cmp_lt_i32_e32 vcc, v3, v1
	s_waitcnt lgkmcnt(0)
	v_add_f32_e32 v2, v4, v2
	v_cndmask_b32_e32 v3, v186, v3, vcc
	v_lshlrev_b32_e32 v15, 2, v3
	ds_bpermute_b32 v3, v15, v2
	ds_bpermute_b32 v4, v15, v0
	s_waitcnt lgkmcnt(1)
	v_add_f32_e32 v2, v2, v3
	v_xor_b32_e32 v3, 4, v186
	v_cmp_lt_i32_e32 vcc, v3, v1
	s_waitcnt lgkmcnt(0)
	v_add_f32_e32 v0, v0, v4
	v_cndmask_b32_e32 v3, v186, v3, vcc
	v_lshlrev_b32_e32 v18, 2, v3
	ds_bpermute_b32 v3, v18, v2
	ds_bpermute_b32 v4, v18, v0
	s_waitcnt lgkmcnt(1)
	v_add_f32_e32 v2, v2, v3
	v_xor_b32_e32 v3, 8, v186
	v_cmp_lt_i32_e32 vcc, v3, v1
	s_waitcnt lgkmcnt(0)
	v_add_f32_e32 v0, v0, v4
	v_cndmask_b32_e32 v3, v186, v3, vcc
	v_lshlrev_b32_e32 v19, 2, v3
	ds_bpermute_b32 v3, v19, v2
	ds_bpermute_b32 v4, v19, v0
	s_waitcnt lgkmcnt(1)
	v_add_f32_e32 v2, v2, v3
	v_xor_b32_e32 v3, 16, v186
	v_cmp_lt_i32_e32 vcc, v3, v1
	s_waitcnt lgkmcnt(0)
	v_add_f32_e32 v0, v0, v4
	v_cndmask_b32_e32 v3, v186, v3, vcc
	v_lshlrev_b32_e32 v80, 2, v3
	ds_bpermute_b32 v3, v80, v2
	ds_bpermute_b32 v4, v80, v0
	s_waitcnt lgkmcnt(1)
	v_add_f32_e32 v2, v2, v3
	v_xor_b32_e32 v3, 32, v186
	v_cmp_lt_i32_e32 vcc, v3, v1
	s_waitcnt lgkmcnt(0)
	v_add_f32_e32 v0, v0, v4
	v_cndmask_b32_e32 v1, v186, v3, vcc
	v_lshlrev_b32_e32 v81, 2, v1
	ds_bpermute_b32 v1, v81, v2
	ds_bpermute_b32 v3, v81, v0
	s_waitcnt lgkmcnt(1)
	v_add_f32_e32 v8, v2, v1
	v_fmamk_f32 v29, v8, 0xba800000, v29
	v_fmac_f32_e32 v28, 0xba800000, v8
	v_fmamk_f32 v31, v8, 0xba800000, v31
	v_fmac_f32_e32 v30, 0xba800000, v8
	s_waitcnt lgkmcnt(0)
; DI void rp_stats2(const f32x4 (&va)[4], const f32x4 (&vb)[4], float& ma, float& ra, float& mb, float& rb) {
;     float sa = 0.f, sb = 0.f;
; #pragma unroll
;     for (int j = 0; j < 4; ++j) { sa += (va[j][0] + va[j][1]) + (va[j][2] + va[j][3]); sb += (vb[j][0] + vb[j][1]) + (vb[j][2] + vb[j][3]); }
;     wave_sum2(sa, sb); ma = sa * (1.0f / DM); mb = sb * (1.0f / DM);
;     float qa = 0.f, qb = 0.f;
; #pragma unroll
;     for (int j = 0; j < 4; ++j) { const f32x4 da = va[j] - ma, db = vb[j] - mb; qa += (da[0] * da[0] + da[1] * da[1]) + (da[2] * da[2] + da[3] * da[3]); qb += (db[0] * db[0] + db[1] * db[1]) + (db[2] * db[2] + db[3] * db[3]); }
;     wave_sum2(qa, qb); ra = 1.0f / sqrtf(qa * (1.0f / DM) + LN_EPS); rb = 1.0f / sqrtf(qb * (1.0f / DM) + LN_EPS);
; }
; DI void rp_ln_store(const RowPass& P, const RowRef& R, f32x4 (&v)[4], float mean, float rstd, int lane) {
; #pragma unroll
;     for (int jj = 0; jj < 4; ++jj) { const int c0 = 4 * lane + 256 * jj; const f32x4 g = *(const f32x4*)(P.lng + c0), bb = *(const f32x4*)(P.lnb + c0); v[jj] = (v[jj] - mean) * rstd * g + bb; }
;     if (R.act && R.xd) {
; #pragma unroll
;         for (int jj = 0; jj < 4; ++jj) *(f32x4*)(R.xd + R.xoff + 4 * lane + 256 * jj) = v[jj];
;     }
; __global__ void __launch_bounds__(512, 2) fwd_kernel(Args a) {
;     ...
;         if (get_rowpass(ph, a, P)) { for (int m = gw; m < ROWS; m += 2 * NGW) { const int m1 = m + NGW; const bool v1 = m1 < ROWS; row_pass2(P, m, v1 ? m1 : m, v1, lane); } }
	v_add_f32_e32 v32, v0, v3
	v_pk_mul_f32 v[0:1], v[30:31], v[30:31]
	v_pk_mul_f32 v[2:3], v[28:29], v[28:29]
	v_fmamk_f32 v13, v32, 0xba800000, v13
	v_pk_mov_b32 v[4:5], v[2:3], v[0:1] op_sel:[1,0]
	v_mov_b32_e32 v3, v1
	v_pk_add_f32 v[0:1], v[4:5], v[2:3]
	v_fmamk_f32 v77, v32, 0xba800000, v77
	v_pk_add_f32 v[0:1], v[0:1], v[0:1] op_sel_hi:[0,1]
	v_fmac_f32_e32 v12, 0xba800000, v32
	v_fmac_f32_e32 v76, 0xba800000, v32
	v_mul_f32_e32 v0, v77, v77
	v_mul_f32_e32 v2, v13, v13
	v_fmac_f32_e32 v0, v76, v76
	v_fmac_f32_e32 v2, v12, v12
	v_fmamk_f32 v25, v8, 0xba800000, v25
	v_fmac_f32_e32 v24, 0xba800000, v8
	v_fmamk_f32 v27, v8, 0xba800000, v27
	v_fmac_f32_e32 v26, 0xba800000, v8
	v_add_f32_e32 v0, v0, v2
	v_pk_mul_f32 v[2:3], v[26:27], v[26:27]
	v_pk_mul_f32 v[4:5], v[24:25], v[24:25]
	v_fmamk_f32 v73, v32, 0xba800000, v73
	v_pk_mov_b32 v[6:7], v[4:5], v[2:3] op_sel:[1,0]
	v_mov_b32_e32 v5, v3
	v_pk_add_f32 v[2:3], v[6:7], v[4:5]
	v_fmamk_f32 v75, v32, 0xba800000, v75
	v_pk_add_f32 v[2:3], v[2:3], v[2:3] op_sel_hi:[0,1]
	v_fmac_f32_e32 v72, 0xba800000, v32
	v_fmac_f32_e32 v74, 0xba800000, v32
	v_mul_f32_e32 v2, v75, v75
	v_mul_f32_e32 v4, v73, v73
	v_fmac_f32_e32 v2, v74, v74
	v_fmac_f32_e32 v4, v72, v72
	v_add_f32_e32 v2, v2, v4
	v_fmac_f32_e32 v20, 0xba800000, v8
	v_add_f32_e32 v2, v0, v2
	v_fmamk_f32 v21, v8, 0xba800000, v21
	v_fmac_f32_e32 v22, 0xba800000, v8
	v_mul_f32_e32 v0, v20, v20
	v_fmamk_f32 v23, v8, 0xba800000, v23
	v_fmamk_f32 v69, v32, 0xba800000, v69
	v_fmamk_f32 v71, v32, 0xba800000, v71
	v_pk_fma_f32 v[4:5], v[20:21], v[20:21], v[0:1] op_sel_hi:[1,1,0]
	v_mul_f32_e32 v0, v22, v22
	v_fmac_f32_e32 v68, 0xba800000, v32
	v_fmac_f32_e32 v70, 0xba800000, v32
	v_pk_fma_f32 v[6:7], v[22:23], v[22:23], v[0:1] op_sel_hi:[1,1,0]
	v_mul_f32_e32 v0, v71, v71
	v_mul_f32_e32 v4, v69, v69
	v_fmac_f32_e32 v0, v70, v70
	v_fmac_f32_e32 v4, v68, v68
	v_add_f32_e32 v0, v0, v4
	v_fmamk_f32 v17, v8, 0xba800000, v17
	v_fmac_f32_e32 v16, 0xba800000, v8
	v_fmamk_f32 v79, v8, 0xba800000, v79
	v_fmac_f32_e32 v78, 0xba800000, v8
	v_add_f32_e32 v82, v0, v2
	v_mul_f32_e32 v4, v78, v78
	v_mul_f32_e32 v6, v79, v79
	v_mul_f32_e32 v0, v16, v16
	v_mul_f32_e32 v2, v17, v17
	v_pk_add_f32 v[4:5], v[4:5], v[6:7]
	v_pk_add_f32 v[0:1], v[0:1], v[2:3]
	v_fmamk_f32 v67, v32, 0xba800000, v67
	v_pk_add_f32 v[0:1], v[4:5], v[0:1]
	v_fmac_f32_e32 v66, 0xba800000, v32
	v_add_f32_e32 v0, v0, v1
	ds_bpermute_b32 v1, v14, v0
	global_load_dwordx4 v[4:7], v[58:59], off
	global_load_dwordx4 v[8:11], v[60:61], off
	global_load_dwordx4 v[36:39], v[58:59], off offset:1024
	global_load_dwordx4 v[40:43], v[60:61], off offset:1024
	v_fmamk_f32 v65, v32, 0xba800000, v65
	v_fmac_f32_e32 v64, 0xba800000, v32
	global_load_dwordx4 v[44:47], v[58:59], off offset:2048
	global_load_dwordx4 v[48:51], v[60:61], off offset:2048
	s_waitcnt lgkmcnt(0)
	v_add_f32_e32 v83, v0, v1
	global_load_dwordx4 v[0:3], v[58:59], off offset:3072
	global_load_dwordx4 v[32:35], v[60:61], off offset:3072
	s_add_i32 s10, s46, s94
	s_cmp_lt_i32 s10, 0x8400
	s_cbranch_scc1 rp_pfa_go
	s_mov_b32 s25, -1
	s_waitcnt vmcnt(0)
	s_branch rp_pfa_end
rp_pfa_go:
	s_mov_b32 s25, s10
	v_readlane_b32 s32, v241, 17
	s_nop 1
	s_add_i32 s32, s10, s32
	s_cmp_lt_i32 s32, 0x8400
	s_cselect_b32 s32, s32, s10
	s_mul_hi_i32 s51, s10, 0x3e0f83e1
	s_lshr_b32 s71, s51, 31
	s_ashr_i32 s51, s51, 11
	s_add_i32 s51, s51, s71
	s_mul_i32 s71, s51, 0x2100
	s_sub_i32 s71, s10, s71
	s_lshl_b32 s51, s51, 8
	s_add_i32 s77, s51, s71
	s_sub_i32 s51, s10, s51
	s_addk_i32 s51, 0xff00
	v_readlane_b32 s54, v241, 29
	v_readlane_b32 s55, v241, 30
	s_cmpk_gt_i32 s71, 0xff
	s_cselect_b32 s77, s51, s77
	s_cselect_b32 s51, 0, s56
	s_cselect_b32 s71, 0, s57
	s_add_u32 s54, s54, s51
	s_addc_u32 s55, s55, s71
	s_lshl_b32 s51, s77, 12
	s_lshr_b32 s77, s77, 20
	s_add_u32 s54, s54, s51
	s_addc_u32 s55, s55, s77
	global_load_dwordx4 v[208:211], v53, s[54:55]
	global_load_dwordx4 v[212:215], v53, s[54:55] offset:1024
	global_load_dwordx4 v[216:219], v53, s[54:55] offset:2048
	global_load_dwordx4 v[220:223], v53, s[54:55] offset:3072
	s_mul_hi_i32 s51, s32, 0x3e0f83e1
	s_lshr_b32 s71, s51, 31
	s_ashr_i32 s51, s51, 11
	s_add_i32 s51, s51, s71
	s_mul_i32 s71, s51, 0x2100
	s_sub_i32 s71, s32, s71
	s_lshl_b32 s51, s51, 8
	s_add_i32 s77, s51, s71
	s_sub_i32 s51, s32, s51
	s_addk_i32 s51, 0xff00
	v_readlane_b32 s54, v241, 29
	v_readlane_b32 s55, v241, 30
	s_cmpk_gt_i32 s71, 0xff
	s_cselect_b32 s77, s51, s77
	s_cselect_b32 s51, 0, s56
	s_cselect_b32 s71, 0, s57
	s_add_u32 s54, s54, s51
	s_addc_u32 s55, s55, s71
	s_lshl_b32 s51, s77, 12
	s_lshr_b32 s77, s77, 20
	s_add_u32 s54, s54, s51
	s_addc_u32 s55, s55, s77
	global_load_dwordx4 v[224:227], v53, s[54:55]
	global_load_dwordx4 v[228:231], v53, s[54:55] offset:1024
	global_load_dwordx4 v[232:235], v53, s[54:55] offset:2048
	global_load_dwordx4 v[236:239], v53, s[54:55] offset:3072
	v_readlane_b32 s54, v241, 37
	v_readlane_b32 s55, v241, 38
	s_lshl_b32 s51, s10, 11
	s_nop 0
	s_add_u32 s54, s54, s51
	s_addc_u32 s55, s55, 0
	global_load_dwordx2 v[190:191], v156, s[54:55]
	global_load_dwordx2 v[192:193], v156, s[54:55] offset:512
	global_load_dwordx2 v[194:195], v156, s[54:55] offset:1024
	global_load_dwordx2 v[196:197], v156, s[54:55] offset:1536
	v_readlane_b32 s54, v241, 37
	v_readlane_b32 s55, v241, 38
	s_lshl_b32 s51, s32, 11
	s_nop 0
	s_add_u32 s54, s54, s51
	s_addc_u32 s55, s55, 0
	global_load_dwordx2 v[198:199], v156, s[54:55]
	global_load_dwordx2 v[200:201], v156, s[54:55] offset:512
	global_load_dwordx2 v[202:203], v156, s[54:55] offset:1024
	global_load_dwordx2 v[158:159], v156, s[54:55] offset:1536
; DI void rp_stats2(const f32x4 (&va)[4], const f32x4 (&vb)[4], float& ma, float& ra, float& mb, float& rb) {
;     float sa = 0.f, sb = 0.f;
; #pragma unroll
;     for (int j = 0; j < 4; ++j) { sa += (va[j][0] + va[j][1]) + (va[j][2] + va[j][3]); sb += (vb[j][0] + vb[j][1]) + (vb[j][2] + vb[j][3]); }
;     wave_sum2(sa, sb); ma = sa * (1.0f / DM); mb = sb * (1.0f / DM);
;     float qa = 0.f, qb = 0.f;
; #pragma unroll
;     for (int j = 0; j < 4; ++j) { const f32x4 da = va[j] - ma, db = vb[j] - mb; qa += (da[0] * da[0] + da[1] * da[1]) + (da[2] * da[2] + da[3] * da[3]); qb += (db[0] * db[0] + db[1] * db[1]) + (db[2] * db[2] + db[3] * db[3]); }
;     wave_sum2(qa, qb); ra = 1.0f / sqrtf(qa * (1.0f / DM) + LN_EPS); rb = 1.0f / sqrtf(qb * (1.0f / DM) + LN_EPS);
; }
; DI void rp_ln_store(const RowPass& P, const RowRef& R, f32x4 (&v)[4], float mean, float rstd, int lane) {
; #pragma unroll
;     for (int jj = 0; jj < 4; ++jj) { const int c0 = 4 * lane + 256 * jj; const f32x4 g = *(const f32x4*)(P.lng + c0), bb = *(const f32x4*)(P.lnb + c0); v[jj] = (v[jj] - mean) * rstd * g + bb; }
;     if (R.act && R.xd) {
; #pragma unroll
;         for (int jj = 0; jj < 4; ++jj) *(f32x4*)(R.xd + R.xoff + 4 * lane + 256 * jj) = v[jj];
;     }
; }
rp_pfa_end:
	ds_bpermute_b32 v84, v15, v83
	v_mul_f32_e32 v85, v65, v65
	v_mul_f32_e32 v86, v67, v67
	v_fmac_f32_e32 v85, v64, v64
	v_fmac_f32_e32 v86, v66, v66
	s_waitcnt lgkmcnt(0)
	v_add_f32_e32 v83, v83, v84
	ds_bpermute_b32 v84, v18, v83
	v_add_f32_e32 v85, v85, v86
	v_add_f32_e32 v82, v85, v82
	ds_bpermute_b32 v14, v14, v82
	s_waitcnt lgkmcnt(1)
	v_add_f32_e32 v83, v83, v84
	ds_bpermute_b32 v84, v19, v83
	s_waitcnt lgkmcnt(1)
	v_add_f32_e32 v14, v82, v14
	ds_bpermute_b32 v15, v15, v14
	s_waitcnt lgkmcnt(1)
	v_add_f32_e32 v82, v83, v84
	ds_bpermute_b32 v83, v80, v82
	s_waitcnt lgkmcnt(1)
	v_add_f32_e32 v14, v14, v15
	ds_bpermute_b32 v15, v18, v14
	s_waitcnt lgkmcnt(1)
	v_add_f32_e32 v18, v82, v83
	ds_bpermute_b32 v82, v81, v18
	s_waitcnt lgkmcnt(1)
	v_add_f32_e32 v14, v14, v15
	ds_bpermute_b32 v15, v19, v14
	s_waitcnt lgkmcnt(1)
	v_add_f32_e32 v18, v18, v82
	v_fmamk_f32 v18, v18, 0x3a800000, v172
	v_mul_f32_e32 v19, 0x4f800000, v18
	v_cmp_gt_f32_e32 vcc, s80, v18
	s_waitcnt lgkmcnt(0)
	v_add_f32_e32 v14, v14, v15
	ds_bpermute_b32 v15, v80, v14
	v_cndmask_b32_e32 v18, v18, v19, vcc
	v_sqrt_f32_e32 v19, v18
	s_waitcnt lgkmcnt(0)
	v_add_f32_e32 v14, v14, v15
	v_add_u32_e32 v80, -1, v19
	v_fma_f32 v82, -v80, v19, v18
	v_cmp_ge_f32_e64 s[0:1], 0, v82
	v_add_u32_e32 v82, 1, v19
	ds_bpermute_b32 v15, v81, v14
	v_cndmask_b32_e64 v80, v19, v80, s[0:1]
	v_fma_f32 v19, -v82, v19, v18
	v_cmp_lt_f32_e64 s[0:1], 0, v19
	s_nop 1
	v_cndmask_b32_e64 v19, v80, v82, s[0:1]
	v_mul_f32_e32 v80, 0x37800000, v19
	v_cndmask_b32_e32 v19, v19, v80, vcc
	v_cmp_class_f32_e32 vcc, v18, v173
	s_nop 1
	v_cndmask_b32_e32 v18, v19, v18, vcc
	v_div_scale_f32 v19, s[0:1], v18, v18, 1.0
	v_rcp_f32_e32 v80, v19
	s_and_b64 s[0:1], s[64:65], s[42:43]
	v_fma_f32 v81, -v19, v80, 1.0
	v_fmac_f32_e32 v80, v81, v80
	v_div_scale_f32 v81, vcc, 1.0, v18, 1.0
	v_mul_f32_e32 v82, v81, v80
	v_fma_f32 v83, -v19, v82, v81
	v_fmac_f32_e32 v82, v83, v80
	v_fma_f32 v19, -v19, v82, v81
	v_div_fmas_f32 v19, v19, v80, v82
	v_div_fixup_f32 v18, v19, v18, 1.0
	v_pk_mul_f32 v[28:29], v[28:29], v[18:19] op_sel_hi:[1,0]
	v_pk_mul_f32 v[30:31], v[30:31], v[18:19] op_sel_hi:[1,0]
	v_pk_mul_f32 v[24:25], v[24:25], v[18:19] op_sel_hi:[1,0]
	v_pk_mul_f32 v[26:27], v[26:27], v[18:19] op_sel_hi:[1,0]
	v_pk_mul_f32 v[20:21], v[20:21], v[18:19] op_sel_hi:[1,0]
	v_pk_mul_f32 v[22:23], v[22:23], v[18:19] op_sel_hi:[1,0]
	v_pk_mul_f32 v[78:79], v[78:79], v[18:19] op_sel_hi:[1,0]
	v_pk_mul_f32 v[16:17], v[16:17], v[18:19] op_sel_hi:[1,0]
	s_waitcnt vmcnt(22)
	v_pk_fma_f32 v[30:31], v[6:7], v[30:31], v[10:11]
	v_pk_fma_f32 v[28:29], v[4:5], v[28:29], v[8:9]
	s_waitcnt vmcnt(20)
	v_pk_fma_f32 v[26:27], v[38:39], v[26:27], v[42:43]
	v_pk_fma_f32 v[24:25], v[36:37], v[24:25], v[40:41]
	s_waitcnt vmcnt(18)
	v_pk_fma_f32 v[22:23], v[46:47], v[22:23], v[50:51]
	v_pk_fma_f32 v[20:21], v[44:45], v[20:21], v[48:49]
	s_waitcnt vmcnt(16)
	v_pk_fma_f32 v[18:19], v[2:3], v[16:17], v[34:35]
	s_andn2_b64 vcc, exec, s[0:1]
	v_pk_fma_f32 v[16:17], v[0:1], v[78:79], v[32:33]
	s_cbranch_vccnz .LBB0_170
	s_lshl_b64 s[0:1], s[90:91], 10
	v_readlane_b32 s4, v241, 33
	v_readlane_b32 s5, v241, 34
	s_add_u32 s4, s4, s92
	s_addc_u32 s5, s5, s93
	s_lshl_b64 s[0:1], s[0:1], 2
	s_add_u32 s0, s4, s0
	s_addc_u32 s1, s5, s1
	global_store_dwordx4 v53, v[28:31], s[0:1]
	global_store_dwordx4 v53, v[24:27], s[0:1] offset:1024
	global_store_dwordx4 v53, v[20:23], s[0:1] offset:2048
	global_store_dwordx4 v53, v[16:19], s[0:1] offset:3072
.LBB0_170:
	s_waitcnt lgkmcnt(0)
	v_add_f32_e32 v14, v14, v15
	v_fmamk_f32 v14, v14, 0x3a800000, v172
	v_mul_f32_e32 v15, 0x4f800000, v14
	v_cmp_gt_f32_e32 vcc, s80, v14
	s_nop 1
	v_cndmask_b32_e32 v14, v14, v15, vcc
	v_sqrt_f32_e32 v15, v14
	s_nop 0
	v_add_u32_e32 v78, -1, v15
	v_add_u32_e32 v79, 1, v15
	v_fma_f32 v80, -v78, v15, v14
	v_fma_f32 v81, -v79, v15, v14
	v_cmp_ge_f32_e64 s[0:1], 0, v80
	s_nop 1
	v_cndmask_b32_e64 v15, v15, v78, s[0:1]
	v_cmp_lt_f32_e64 s[0:1], 0, v81
	s_nop 1
	v_cndmask_b32_e64 v15, v15, v79, s[0:1]
	v_mul_f32_e32 v78, 0x37800000, v15
	v_cndmask_b32_e32 v15, v15, v78, vcc
	v_cmp_class_f32_e32 vcc, v14, v173
	s_nop 1
	v_cndmask_b32_e32 v14, v15, v14, vcc
	v_div_scale_f32 v15, s[0:1], v14, v14, 1.0
	v_rcp_f32_e32 v78, v15
	s_and_b64 s[0:1], s[60:61], s[42:43]
	v_fma_f32 v79, -v15, v78, 1.0
	v_fmac_f32_e32 v78, v79, v78
	v_div_scale_f32 v79, vcc, 1.0, v14, 1.0
	v_mul_f32_e32 v80, v79, v78
	v_fma_f32 v81, -v15, v80, v79
	v_fmac_f32_e32 v80, v81, v78
	v_fma_f32 v15, -v15, v80, v79
	v_div_fmas_f32 v15, v15, v78, v80
	v_div_fixup_f32 v78, v15, v14, 1.0
	v_pk_mul_f32 v[76:77], v[76:77], v[78:79] op_sel_hi:[1,0]
	v_pk_mul_f32 v[12:13], v[12:13], v[78:79] op_sel_hi:[1,0]
	s_andn2_b64 vcc, exec, s[0:1]
	v_pk_fma_f32 v[14:15], v[12:13], v[6:7], v[10:11]
	v_pk_fma_f32 v[12:13], v[76:77], v[4:5], v[8:9]
	v_pk_mul_f32 v[4:5], v[74:75], v[78:79] op_sel_hi:[1,0]
	v_pk_mul_f32 v[6:7], v[72:73], v[78:79] op_sel_hi:[1,0]
	v_pk_fma_f32 v[8:9], v[4:5], v[36:37], v[40:41]
	v_pk_fma_f32 v[10:11], v[6:7], v[38:39], v[42:43]
	v_pk_mul_f32 v[4:5], v[70:71], v[78:79] op_sel_hi:[1,0]
	v_pk_mul_f32 v[6:7], v[68:69], v[78:79] op_sel_hi:[1,0]
	v_pk_mul_f32 v[36:37], v[64:65], v[78:79] op_sel_hi:[1,0]
	v_pk_mul_f32 v[38:39], v[66:67], v[78:79] op_sel_hi:[1,0]
	v_pk_fma_f32 v[6:7], v[6:7], v[46:47], v[50:51]
	v_pk_fma_f32 v[4:5], v[4:5], v[44:45], v[48:49]
	v_pk_fma_f32 v[2:3], v[38:39], v[2:3], v[34:35]
	v_pk_fma_f32 v[0:1], v[36:37], v[0:1], v[32:33]
	s_cbranch_vccnz .LBB0_172
	s_lshl_b64 s[0:1], s[66:67], 10
	v_readlane_b32 s4, v241, 33
	v_readlane_b32 s5, v241, 34
	s_add_u32 s4, s4, s84
	s_addc_u32 s5, s5, s85
	s_lshl_b64 s[0:1], s[0:1], 2
	s_add_u32 s0, s4, s0
	s_addc_u32 s1, s5, s1
	global_store_dwordx4 v53, v[12:15], s[0:1]
	global_store_dwordx4 v53, v[8:11], s[0:1] offset:1024
	global_store_dwordx4 v53, v[4:7], s[0:1] offset:2048
	global_store_dwordx4 v53, v[0:3], s[0:1] offset:3072
; DI void rp_stats2(const f32x4 (&va)[4], const f32x4 (&vb)[4], float& ma, float& ra, float& mb, float& rb) {
;     float sa = 0.f, sb = 0.f;
; #pragma unroll
;     for (int j = 0; j < 4; ++j) { sa += (va[j][0] + va[j][1]) + (va[j][2] + va[j][3]); sb += (vb[j][0] + vb[j][1]) + (vb[j][2] + vb[j][3]); }
;     wave_sum2(sa, sb); ma = sa * (1.0f / DM); mb = sb * (1.0f / DM);
;     float qa = 0.f, qb = 0.f;
; #pragma unroll
;     for (int j = 0; j < 4; ++j) { const f32x4 da = va[j] - ma, db = vb[j] - mb; qa += (da[0] * da[0] + da[1] * da[1]) + (da[2] * da[2] + da[3] * da[3]); qb += (db[0] * db[0] + db[1] * db[1]) + (db[2] * db[2] + db[3] * db[3]); }
;     wave_sum2(qa, qb); ra = 1.0f / sqrtf(qa * (1.0f / DM) + LN_EPS); rb = 1.0f / sqrtf(qb * (1.0f / DM) + LN_EPS);
; }
; DI void row_pass2(const RowPass& P, int m0, int m1, bool act1, int lane) {
;     ...
;     if (P.H) {
;         float ma, ra, mb, rb; rp_stats2(va, vb, ma, ra, mb, rb);
.LBB0_172:
	s_andn2_b64 vcc, exec, s[44:45]
	s_cbranch_vccnz .LBB0_157
	v_mov_b32_e32 v32, v29
	v_mov_b32_e32 v33, v30
	v_mov_b32_e32 v34, v28
	v_mov_b32_e32 v35, v31
	v_pk_add_f32 v[32:33], v[32:33], v[34:35]
	v_mov_b32_e32 v34, v13
	v_mov_b32_e32 v35, v14
	v_mov_b32_e32 v36, v12
	v_mov_b32_e32 v37, v15
	v_pk_add_f32 v[34:35], v[34:35], v[36:37]
	v_mov_b32_e32 v36, v25
	v_mov_b32_e32 v37, v26
	v_mov_b32_e32 v38, v24
	v_mov_b32_e32 v39, v27
	v_add_f32_e32 v32, v32, v33
	v_pk_add_f32 v[36:37], v[36:37], v[38:39]
	v_add_f32_e32 v33, 0, v32
	v_add_f32_e32 v32, v34, v35
	v_pk_add_f32 v[36:37], v[36:37], v[36:37] op_sel_hi:[0,1]
	v_mov_b32_e32 v38, v9
	v_mov_b32_e32 v39, v10
	v_mov_b32_e32 v40, v8
	v_mov_b32_e32 v41, v11
	v_add_f32_e32 v35, 0, v32
	v_pk_add_f32 v[38:39], v[38:39], v[40:41]
	v_add_f32_e32 v41, v20, v21
	v_add_f32_e32 v43, v22, v23
	v_mov_b32_e32 v40, v16
	v_mov_b32_e32 v42, v17
	v_mov_b32_e32 v36, v18
	v_mov_b32_e32 v32, v19
	v_pk_add_f32 v[38:39], v[38:39], v[38:39] op_sel_hi:[0,1]
	v_pk_add_f32 v[40:41], v[40:41], v[42:43]
	v_pk_add_f32 v[32:33], v[36:37], v[32:33]
	v_add_f32_e32 v45, v4, v5
	v_add_f32_e32 v47, v6, v7
	v_pk_add_f32 v[32:33], v[40:41], v[32:33]
	v_mov_b32_e32 v44, v0
	v_mov_b32_e32 v46, v1
	v_mov_b32_e32 v38, v2
	v_mov_b32_e32 v34, v3
	v_add_f32_e32 v36, v32, v33
	v_pk_add_f32 v[32:33], v[44:45], v[46:47]
	v_pk_add_f32 v[34:35], v[38:39], v[34:35]
	s_nop 0
	v_pk_add_f32 v[32:33], v[32:33], v[34:35]
	v_xor_b32_e32 v34, 1, v186
	v_add_f32_e32 v32, v32, v33
	v_and_b32_e32 v33, 64, v186
	v_add_u32_e32 v33, 64, v33
	v_cmp_lt_i32_e32 vcc, v34, v33
	s_nop 1
	v_cndmask_b32_e32 v34, v186, v34, vcc
	v_lshlrev_b32_e32 v34, 2, v34
	ds_bpermute_b32 v35, v34, v36
	ds_bpermute_b32 v37, v34, v32
	s_waitcnt lgkmcnt(1)
	v_add_f32_e32 v35, v36, v35
	v_xor_b32_e32 v36, 2, v186
	v_cmp_lt_i32_e32 vcc, v36, v33
	s_waitcnt lgkmcnt(0)
	v_add_f32_e32 v32, v32, v37
	v_cndmask_b32_e32 v36, v186, v36, vcc
	v_lshlrev_b32_e32 v36, 2, v36
	ds_bpermute_b32 v37, v36, v35
	ds_bpermute_b32 v38, v36, v32
	s_waitcnt lgkmcnt(1)
	v_add_f32_e32 v35, v35, v37
	v_xor_b32_e32 v37, 4, v186
	v_cmp_lt_i32_e32 vcc, v37, v33
	s_waitcnt lgkmcnt(0)
	v_add_f32_e32 v32, v32, v38
	v_cndmask_b32_e32 v37, v186, v37, vcc
	v_lshlrev_b32_e32 v37, 2, v37
	ds_bpermute_b32 v38, v37, v35
	ds_bpermute_b32 v39, v37, v32
	s_waitcnt lgkmcnt(1)
	v_add_f32_e32 v35, v35, v38
	v_xor_b32_e32 v38, 8, v186
	v_cmp_lt_i32_e32 vcc, v38, v33
	s_waitcnt lgkmcnt(0)
	v_add_f32_e32 v32, v32, v39
	v_cndmask_b32_e32 v38, v186, v38, vcc
	v_lshlrev_b32_e32 v38, 2, v38
	ds_bpermute_b32 v39, v38, v35
	ds_bpermute_b32 v40, v38, v32
	s_waitcnt lgkmcnt(1)
	v_add_f32_e32 v35, v35, v39
	v_xor_b32_e32 v39, 16, v186
	v_cmp_lt_i32_e32 vcc, v39, v33
	s_waitcnt lgkmcnt(0)
	v_add_f32_e32 v32, v32, v40
	v_cndmask_b32_e32 v39, v186, v39, vcc
	v_lshlrev_b32_e32 v39, 2, v39
	ds_bpermute_b32 v40, v39, v35
	ds_bpermute_b32 v41, v39, v32
	s_waitcnt lgkmcnt(1)
	v_add_f32_e32 v35, v35, v40
	v_xor_b32_e32 v40, 32, v186
	v_cmp_lt_i32_e32 vcc, v40, v33
	s_waitcnt lgkmcnt(0)
	v_add_f32_e32 v32, v32, v41
	v_cndmask_b32_e32 v33, v186, v40, vcc
	v_lshlrev_b32_e32 v33, 2, v33
	ds_bpermute_b32 v40, v33, v35
	ds_bpermute_b32 v41, v33, v32
	s_andn2_b64 vcc, exec, s[64:65]
	s_waitcnt lgkmcnt(1)
	v_add_f32_e32 v35, v35, v40
	v_fmac_f32_e32 v31, 0xba800000, v35
	v_fmac_f32_e32 v29, 0xba800000, v35
	s_waitcnt lgkmcnt(0)
	v_add_f32_e32 v32, v32, v41
	v_fmac_f32_e32 v30, 0xba800000, v35
	v_fmac_f32_e32 v28, 0xba800000, v35
	v_mul_f32_e32 v40, v29, v29
	v_mul_f32_e32 v41, v31, v31
	v_fmac_f32_e32 v15, 0xba800000, v32
	v_fmac_f32_e32 v13, 0xba800000, v32
	v_fmac_f32_e32 v40, v28, v28
	v_fmac_f32_e32 v41, v30, v30
	v_fmac_f32_e32 v14, 0xba800000, v32
	v_fmac_f32_e32 v12, 0xba800000, v32
	v_add_f32_e32 v40, v40, v41
	v_mul_f32_e32 v41, v13, v13
	v_mul_f32_e32 v42, v15, v15
	v_fmac_f32_e32 v41, v12, v12
	v_fmac_f32_e32 v42, v14, v14
	v_fmac_f32_e32 v27, 0xba800000, v35
	v_fmac_f32_e32 v25, 0xba800000, v35
	v_add_f32_e32 v41, v41, v42
	v_fmac_f32_e32 v26, 0xba800000, v35
	v_fmac_f32_e32 v24, 0xba800000, v35
	v_mul_f32_e32 v42, v25, v25
	v_mul_f32_e32 v43, v27, v27
	v_fmac_f32_e32 v42, v24, v24
	v_fmac_f32_e32 v43, v26, v26
	v_fmac_f32_e32 v11, 0xba800000, v32
	v_fmac_f32_e32 v9, 0xba800000, v32
	v_add_f32_e32 v42, v42, v43
	v_fmac_f32_e32 v10, 0xba800000, v32
	v_fmac_f32_e32 v8, 0xba800000, v32
	v_add_f32_e32 v40, v40, v42
	v_mul_f32_e32 v42, v9, v9
	v_mul_f32_e32 v43, v11, v11
	v_fmac_f32_e32 v42, v8, v8
	v_fmac_f32_e32 v43, v10, v10
	v_add_f32_e32 v42, v42, v43
	v_fmac_f32_e32 v23, 0xba800000, v35
	v_fmac_f32_e32 v21, 0xba800000, v35
	v_add_f32_e32 v41, v41, v42
	v_fmac_f32_e32 v22, 0xba800000, v35
	v_fmac_f32_e32 v20, 0xba800000, v35
	v_mul_f32_e32 v42, v21, v21
	v_mul_f32_e32 v43, v23, v23
	v_fmac_f32_e32 v19, 0xba800000, v35
	v_fmac_f32_e32 v17, 0xba800000, v35
	v_fmac_f32_e32 v7, 0xba800000, v32
	v_fmac_f32_e32 v6, 0xba800000, v32
	v_fmac_f32_e32 v5, 0xba800000, v32
	v_fmac_f32_e32 v4, 0xba800000, v32
	v_fmac_f32_e32 v42, v20, v20
	v_fmac_f32_e32 v43, v22, v22
	v_fmac_f32_e32 v18, 0xba800000, v35
	v_fmac_f32_e32 v16, 0xba800000, v35
	v_fmac_f32_e32 v3, 0xba800000, v32
	v_fmac_f32_e32 v2, 0xba800000, v32
	v_fmac_f32_e32 v1, 0xba800000, v32
	v_fmac_f32_e32 v0, 0xba800000, v32
	v_mul_f32_e32 v32, v17, v17
	v_mul_f32_e32 v35, v19, v19
	v_add_f32_e32 v42, v42, v43
	v_fmac_f32_e32 v32, v16, v16
	v_fmac_f32_e32 v35, v18, v18
	v_add_f32_e32 v40, v42, v40
	v_mul_f32_e32 v42, v5, v5
	v_mul_f32_e32 v43, v7, v7
	v_add_f32_e32 v32, v32, v35
	v_fmac_f32_e32 v42, v4, v4
	v_fmac_f32_e32 v43, v6, v6
	v_add_f32_e32 v32, v32, v40
	v_mul_f32_e32 v35, v1, v1
	v_mul_f32_e32 v40, v3, v3
	v_add_f32_e32 v42, v42, v43
	v_fmac_f32_e32 v35, v0, v0
	v_fmac_f32_e32 v40, v2, v2
	v_add_f32_e32 v41, v42, v41
	v_add_f32_e32 v35, v35, v40
	v_add_f32_e32 v35, v35, v41
	ds_bpermute_b32 v40, v34, v32
	ds_bpermute_b32 v34, v34, v35
	s_waitcnt lgkmcnt(1)
	v_add_f32_e32 v32, v32, v40
	s_waitcnt lgkmcnt(0)
	v_add_f32_e32 v34, v35, v34
	ds_bpermute_b32 v35, v36, v32
	ds_bpermute_b32 v36, v36, v34
	s_waitcnt lgkmcnt(1)
	v_add_f32_e32 v32, v32, v35
	s_waitcnt lgkmcnt(0)
	v_add_f32_e32 v34, v34, v36
	ds_bpermute_b32 v35, v37, v32
	ds_bpermute_b32 v36, v37, v34
	s_waitcnt lgkmcnt(1)
	v_add_f32_e32 v32, v32, v35
	s_waitcnt lgkmcnt(0)
	v_add_f32_e32 v34, v34, v36
	ds_bpermute_b32 v35, v38, v32
	ds_bpermute_b32 v36, v38, v34
	s_waitcnt lgkmcnt(1)
	v_add_f32_e32 v32, v32, v35
	s_waitcnt lgkmcnt(0)
	v_add_f32_e32 v35, v34, v36
	ds_bpermute_b32 v34, v39, v32
	ds_bpermute_b32 v36, v39, v35
	s_waitcnt lgkmcnt(1)
	v_add_f32_e32 v34, v32, v34
	s_waitcnt lgkmcnt(0)
	v_add_f32_e32 v32, v35, v36
	ds_bpermute_b32 v35, v33, v34
	ds_bpermute_b32 v33, v33, v32
	s_cbranch_vccnz .LBB0_175
; DI unsigned cvtpk(float lo, float hi) { f32x2 v = {lo, hi}; bf16x2_t b = __builtin_convertvector(v, bf16x2_t); return __builtin_bit_cast(unsigned, b); }
; DI void rp_h_store(const RowPass& P, const RowRef& R, const f32x4 (&v)[4], float mean, float rstd, int lane) {
;     if (!R.act) return;
;     const float* sc = P.mod2 + (size_t)R.cls * 6144 + P.sc_off; const float* sh = P.mod2 + (size_t)R.cls * 6144 + P.sh_off;
; #pragma unroll
;     for (int jj = 0; jj < 4; ++jj) { const int c0 = 4 * lane + 256 * jj; const f32x4 s1 = *(const f32x4*)(sc + c0), s0 = *(const f32x4*)(sh + c0);
;         const f32x4 hh = (v[jj] - mean) * rstd * (s1 + 1.0f) + s0; u32x2 w; w.x = cvtpk(hh[0], hh[1]); w.y = cvtpk(hh[2], hh[3]);
;         *(u32x2*)(P.H + (size_t)R.m * DM + c0) = w; }
; }
	v_readlane_b32 s0, v241, 45
	v_readlane_b32 s1, v241, 46
	s_add_u32 s4, s0, s62
	s_addc_u32 s5, s1, s63
	v_readlane_b32 s0, v242, 11
	v_readlane_b32 s1, v242, 12
	s_lshl_b64 s[0:1], s[0:1], 2
	s_add_u32 s26, s4, s0
	s_addc_u32 s27, s5, s1
	v_readlane_b32 s0, v242, 9
	v_readlane_b32 s1, v242, 10
	s_lshl_b64 s[0:1], s[0:1], 2
	s_add_u32 s38, s4, s0
	global_load_dwordx4 v[36:39], v53, s[26:27]
	s_addc_u32 s39, s5, s1
	global_load_dwordx4 v[40:43], v53, s[38:39]
	s_waitcnt lgkmcnt(1)
	v_add_f32_e32 v34, v34, v35
	v_fmamk_f32 v34, v34, 0x3a800000, v172
	v_mul_f32_e32 v35, 0x4f800000, v34
	v_cmp_gt_f32_e32 vcc, s80, v34
	s_ashr_i32 s47, s46, 31
	s_lshl_b64 s[4:5], s[46:47], 11
	v_cndmask_b32_e32 v34, v34, v35, vcc
	v_sqrt_f32_e32 v35, v34
	s_waitcnt vmcnt(1)
	v_pk_add_f32 v[36:37], v[36:37], 1.0 op_sel_hi:[1,0]
	v_add_u32_e32 v44, -1, v35
	v_add_u32_e32 v45, 1, v35
	v_fma_f32 v46, -v44, v35, v34
	v_fma_f32 v47, -v45, v35, v34
	v_cmp_ge_f32_e64 s[0:1], 0, v46
	s_nop 1
	v_cndmask_b32_e64 v35, v35, v44, s[0:1]
	v_cmp_lt_f32_e64 s[0:1], 0, v47
	s_nop 1
	v_cndmask_b32_e64 v35, v35, v45, s[0:1]
	v_mul_f32_e32 v44, 0x37800000, v35
	v_cndmask_b32_e32 v35, v35, v44, vcc
	v_cmp_class_f32_e32 vcc, v34, v173
	v_lshl_add_u64 v[44:45], v[62:63], 0, s[4:5]
	s_nop 0
	v_cndmask_b32_e32 v34, v35, v34, vcc
	v_div_scale_f32 v35, s[0:1], v34, v34, 1.0
	v_rcp_f32_e32 v46, v35
	v_div_scale_f32 v47, vcc, 1.0, v34, 1.0
	v_fma_f32 v48, -v35, v46, 1.0
	v_fmac_f32_e32 v46, v48, v46
	v_mul_f32_e32 v48, v47, v46
	v_fma_f32 v49, -v35, v48, v47
	v_fmac_f32_e32 v48, v49, v46
	v_fma_f32 v35, -v35, v48, v47
	v_div_fmas_f32 v35, v35, v46, v48
	v_div_fixup_f32 v46, v35, v34, 1.0
	v_pk_mul_f32 v[28:29], v[28:29], v[46:47] op_sel_hi:[1,0]
	v_pk_mul_f32 v[30:31], v[30:31], v[46:47] op_sel_hi:[1,0]
	v_pk_add_f32 v[34:35], v[38:39], 1.0 op_sel_hi:[1,0]
	s_waitcnt vmcnt(0)
	v_pk_fma_f32 v[28:29], v[28:29], v[36:37], v[40:41]
	v_pk_fma_f32 v[30:31], v[30:31], v[34:35], v[42:43]
	v_cvt_pk_bf16_f32 v28, v28, v29
	v_cvt_pk_bf16_f32 v29, v30, v31
	global_store_dwordx2 v[44:45], v[28:29], off
	global_load_dwordx4 v[28:31], v53, s[26:27] offset:1024
	s_nop 0
	global_load_dwordx4 v[34:37], v53, s[38:39] offset:1024
	v_pk_mul_f32 v[24:25], v[24:25], v[46:47] op_sel_hi:[1,0]
	v_pk_mul_f32 v[26:27], v[26:27], v[46:47] op_sel_hi:[1,0]
	v_pk_mul_f32 v[20:21], v[20:21], v[46:47] op_sel_hi:[1,0]
	v_pk_mul_f32 v[22:23], v[22:23], v[46:47] op_sel_hi:[1,0]
	v_pk_mul_f32 v[16:17], v[16:17], v[46:47] op_sel_hi:[1,0]
	v_pk_mul_f32 v[18:19], v[18:19], v[46:47] op_sel_hi:[1,0]
	s_waitcnt vmcnt(1)
	v_pk_add_f32 v[30:31], v[30:31], 1.0 op_sel_hi:[1,0]
	v_pk_add_f32 v[28:29], v[28:29], 1.0 op_sel_hi:[1,0]
	s_waitcnt vmcnt(0)
	v_pk_fma_f32 v[26:27], v[26:27], v[30:31], v[36:37]
	v_pk_fma_f32 v[24:25], v[24:25], v[28:29], v[34:35]
	s_nop 0
	v_cvt_pk_bf16_f32 v24, v24, v25
	v_cvt_pk_bf16_f32 v25, v26, v27
	global_store_dwordx2 v[44:45], v[24:25], off offset:512
	global_load_dwordx4 v[24:27], v53, s[26:27] offset:2048
	s_nop 0
	global_load_dwordx4 v[28:31], v53, s[38:39] offset:2048
	s_waitcnt vmcnt(1)
	v_pk_add_f32 v[26:27], v[26:27], 1.0 op_sel_hi:[1,0]
	v_pk_add_f32 v[24:25], v[24:25], 1.0 op_sel_hi:[1,0]
	s_waitcnt vmcnt(0)
	v_pk_fma_f32 v[22:23], v[22:23], v[26:27], v[30:31]
	v_pk_fma_f32 v[20:21], v[20:21], v[24:25], v[28:29]
	s_nop 0
	v_cvt_pk_bf16_f32 v20, v20, v21
	v_cvt_pk_bf16_f32 v21, v22, v23
	global_store_dwordx2 v[44:45], v[20:21], off offset:1024
	global_load_dwordx4 v[20:23], v53, s[26:27] offset:3072
	s_nop 0
	global_load_dwordx4 v[24:27], v53, s[38:39] offset:3072
	s_waitcnt vmcnt(1)
	v_pk_add_f32 v[22:23], v[22:23], 1.0 op_sel_hi:[1,0]
	v_pk_add_f32 v[20:21], v[20:21], 1.0 op_sel_hi:[1,0]
	s_waitcnt vmcnt(0)
	v_pk_fma_f32 v[18:19], v[18:19], v[22:23], v[26:27]
	v_pk_fma_f32 v[16:17], v[16:17], v[20:21], v[24:25]
	s_nop 0
	v_cvt_pk_bf16_f32 v16, v16, v17
	v_cvt_pk_bf16_f32 v17, v18, v19
	global_store_dwordx2 v[44:45], v[16:17], off offset:1536

; DI void rp_load(const RowRef& R, f32x4 (&v)[4], int lane) {
; #pragma unroll
;     for (int jj = 0; jj < 4; ++jj) v[jj] = *(const f32x4*)(R.xs + 4 * lane + 256 * jj);
; __global__ void __launch_bounds__(512, 2) fwd_kernel(Args a) {
;     ...
;         if (get_rowpass(ph, a, P)) { for (int m = gw; m < ROWS; m += 2 * NGW) { const int m1 = m + NGW; const bool v1 = m1 < ROWS; row_pass2(P, m, v1 ? m1 : m, v1, lane); } }
rp_noy_wait:
	s_waitcnt vmcnt(0)
	s_add_i32 s10, s46, s94
	s_cmp_lt_i32 s10, 0x8400
	s_cbranch_scc1 rp_pfb_go
	s_mov_b32 s25, -1
	s_waitcnt vmcnt(0)
	s_branch rp_pfb_end
rp_pfb_go:
	s_mov_b32 s25, s10
	v_readlane_b32 s32, v241, 17
	s_nop 1
	s_add_i32 s32, s10, s32
	s_cmp_lt_i32 s32, 0x8400
	s_cselect_b32 s32, s32, s10
	s_mul_hi_i32 s51, s10, 0x3e0f83e1
	s_lshr_b32 s71, s51, 31
	s_ashr_i32 s51, s51, 11
	s_add_i32 s51, s51, s71
	s_mul_i32 s71, s51, 0x2100
	s_sub_i32 s71, s10, s71
	s_lshl_b32 s51, s51, 8
	s_add_i32 s77, s51, s71
	s_sub_i32 s51, s10, s51
	s_addk_i32 s51, 0xff00
	v_readlane_b32 s54, v241, 29
	v_readlane_b32 s55, v241, 30
	s_cmpk_gt_i32 s71, 0xff
	s_cselect_b32 s77, s51, s77
	s_cselect_b32 s51, 0, s56
	s_cselect_b32 s71, 0, s57
	s_add_u32 s54, s54, s51
	s_addc_u32 s55, s55, s71
	s_lshl_b32 s51, s77, 12
	s_lshr_b32 s77, s77, 20
	s_add_u32 s54, s54, s51
	s_addc_u32 s55, s55, s77
	global_load_dwordx4 v[208:211], v53, s[54:55]
	global_load_dwordx4 v[212:215], v53, s[54:55] offset:1024
	global_load_dwordx4 v[216:219], v53, s[54:55] offset:2048
	global_load_dwordx4 v[220:223], v53, s[54:55] offset:3072
	s_mul_hi_i32 s51, s32, 0x3e0f83e1
	s_lshr_b32 s71, s51, 31
	s_ashr_i32 s51, s51, 11
	s_add_i32 s51, s51, s71
	s_mul_i32 s71, s51, 0x2100
	s_sub_i32 s71, s32, s71
	s_lshl_b32 s51, s51, 8
	s_add_i32 s77, s51, s71
	s_sub_i32 s51, s32, s51
	s_addk_i32 s51, 0xff00
	v_readlane_b32 s54, v241, 29
	v_readlane_b32 s55, v241, 30
	s_cmpk_gt_i32 s71, 0xff
	s_cselect_b32 s77, s51, s77
	s_cselect_b32 s51, 0, s56
	s_cselect_b32 s71, 0, s57
	s_add_u32 s54, s54, s51
	s_addc_u32 s55, s55, s71
	s_lshl_b32 s51, s77, 12
	s_lshr_b32 s77, s77, 20
	s_add_u32 s54, s54, s51
	s_addc_u32 s55, s55, s77
	global_load_dwordx4 v[224:227], v53, s[54:55]
	global_load_dwordx4 v[228:231], v53, s[54:55] offset:1024
	global_load_dwordx4 v[232:235], v53, s[54:55] offset:2048
	global_load_dwordx4 v[236:239], v53, s[54:55] offset:3072
rp_pfb_end:
	s_branch .LBB0_172
.LBB0_177:
	s_waitcnt vmcnt(0)
	v_readlane_b32 s90, v241, 25
	v_readlane_b32 s91, v241, 26
	s_cmp_lt_i32 s69, 12
	s_mov_b64 s[0:1], -1
	v_readlane_b32 s10, v243, 58
	s_cbranch_scc1 .LBB0_253
	s_cmp_lt_i32 s69, 18
	s_cbranch_scc1 .LBB0_185
	s_cmp_eq_u32 s69, 18
	s_cbranch_scc0 .LBB0_184
	s_cmpk_gt_i32 s76, 0x7ff
	s_cbranch_scc1 .LBB0_184
	s_bfe_u32 s0, s13, 0x20006
	s_mul_i32 s1, s0, 0x4200
	s_add_u32 s4, s16, s1
	s_addc_u32 s5, s17, 0
	s_lshl_b32 s0, s0, 12
	v_readlane_b32 s1, v244, 3
	s_waitcnt vmcnt(0)
	v_lshlrev_b32_e32 v2, 3, v189
	s_add_u32 s0, s1, s0
	v_readlane_b32 s1, v244, 4
	v_or_b32_e32 v4, 0x200, v2
	v_or_b32_e32 v6, 0x400, v2
	s_waitcnt lgkmcnt(0)
	v_or_b32_e32 v8, 0x600, v2
	s_addc_u32 s1, s1, 0
	v_lshlrev_b32_e32 v156, 4, v189
	s_mov_b64 s[42:43], s[22:23]
	s_mov_b64 s[40:41], s[34:35]
	v_lshl_add_u64 v[0:1], s[0:1], 0, v[156:157]
	v_lshlrev_b32_e32 v156, 1, v2
	v_lshlrev_b32_e32 v2, 1, v4
	v_lshlrev_b32_e32 v4, 1, v6
	v_lshlrev_b32_e32 v6, 1, v8
	s_mov_b32 s25, s76
	s_mov_b32 s38, 0x3000000
	v_readlane_b32 s44, v241, 17
	v_readlane_b32 s45, v241, 18
